# attention: P@V tr_read waits counted per MFMA (lgkmcnt 6) instead of draining per group; waves 4-7 sleep ~768 clk after each tile-start barrier so their QK/softmax/PV interleave with waves 0-3
# speedup vs baseline: 1.0125x; 1.0068x over previous
.LBB0_567:
	s_barrier
	v_readfirstlane_b32 s100, v0
	s_nop 3
	s_cmp_lt_u32 s100, 0x100
	s_cbranch_scc1 .Lstg_1
	s_sleep 12
.Lstg_1:
	ds_read_b128 v[194:197], v238
	ds_read_b128 v[198:201], v239
	ds_read_b128 v[202:205], v238 offset:8192
	ds_read_b128 v[206:209], v239 offset:8192
	s_waitcnt lgkmcnt(3)
	v_mfma_f32_32x32x16_bf16 v[146:161], v[194:197], v[162:165], 0
	ds_read_b128 v[194:197], v240
	s_waitcnt lgkmcnt(3)
	v_mfma_f32_32x32x16_bf16 v[146:161], v[198:201], v[166:169], v[146:161]
	s_cmp_lt_u32 s97, 5
	s_cbranch_scc1 .Lad1a_0
	s_mov_b64 s[100:101], 0xc0000
	s_mov_b32 m0, s77
	v_lshl_add_u64 v[250:251], v[222:223], 0, s[100:101]
	global_load_lds_dwordx4 v[250:251], off

.LBB0_571:
	v_cndmask_b32_e64 v249, v220, v249, s[6:7]
	v_mul_f32_e32 v194, 0xbe0293ee, v249
	v_fmamk_f32 v146, v146, 0x3e0293ee, v194
	v_fmamk_f32 v147, v147, 0x3e0293ee, v194
	v_fmamk_f32 v148, v148, 0x3e0293ee, v194
	v_fmamk_f32 v149, v149, 0x3e0293ee, v194
	v_fmamk_f32 v150, v150, 0x3e0293ee, v194
	v_fmamk_f32 v151, v151, 0x3e0293ee, v194
	v_fmamk_f32 v152, v152, 0x3e0293ee, v194
	v_fmamk_f32 v153, v153, 0x3e0293ee, v194
	v_fmamk_f32 v154, v154, 0x3e0293ee, v194
	v_fmamk_f32 v155, v155, 0x3e0293ee, v194
	v_fmamk_f32 v156, v156, 0x3e0293ee, v194
	v_fmamk_f32 v157, v157, 0x3e0293ee, v194
	v_fmamk_f32 v158, v158, 0x3e0293ee, v194
	v_fmamk_f32 v159, v159, 0x3e0293ee, v194
	v_fmamk_f32 v160, v160, 0x3e0293ee, v194
	v_fmamk_f32 v161, v161, 0x3e0293ee, v194
	v_fmamk_f32 v130, v130, 0x3e0293ee, v194
	v_fmamk_f32 v131, v131, 0x3e0293ee, v194
	v_fmamk_f32 v132, v132, 0x3e0293ee, v194
	v_fmamk_f32 v133, v133, 0x3e0293ee, v194
	v_fmamk_f32 v134, v134, 0x3e0293ee, v194
	v_fmamk_f32 v135, v135, 0x3e0293ee, v194
	v_fmamk_f32 v136, v136, 0x3e0293ee, v194
	v_fmamk_f32 v137, v137, 0x3e0293ee, v194
	v_fmamk_f32 v138, v138, 0x3e0293ee, v194
	v_fmamk_f32 v139, v139, 0x3e0293ee, v194
	v_fmamk_f32 v140, v140, 0x3e0293ee, v194
	v_fmamk_f32 v141, v141, 0x3e0293ee, v194
	v_fmamk_f32 v142, v142, 0x3e0293ee, v194
	v_fmamk_f32 v143, v143, 0x3e0293ee, v194
	v_fmamk_f32 v144, v144, 0x3e0293ee, v194
	v_fmac_f32_e32 v194, 0x3e0293ee, v145
	v_exp_f32_e32 v145, v146
	v_exp_f32_e32 v146, v147
	v_exp_f32_e32 v147, v148
	v_exp_f32_e32 v148, v149
	v_exp_f32_e32 v149, v150
	v_exp_f32_e32 v150, v151
	v_exp_f32_e32 v151, v152
	v_exp_f32_e32 v152, v153
	v_exp_f32_e32 v153, v154
	v_exp_f32_e32 v154, v155
	v_exp_f32_e32 v155, v156
	v_exp_f32_e32 v156, v157
	v_exp_f32_e32 v157, v158
	v_exp_f32_e32 v158, v159
	v_exp_f32_e32 v159, v160
	v_exp_f32_e32 v160, v161
	v_exp_f32_e32 v161, v130
	v_add_f32_e32 v130, 0, v145
	v_add_f32_e32 v130, v146, v130
	v_add_f32_e32 v130, v147, v130
	v_add_f32_e32 v130, v148, v130
	v_add_f32_e32 v130, v149, v130
	v_add_f32_e32 v130, v150, v130
	v_add_f32_e32 v130, v151, v130
	v_add_f32_e32 v130, v152, v130
	v_add_f32_e32 v130, v153, v130
	v_add_f32_e32 v130, v154, v130
	v_add_f32_e32 v130, v155, v130
	v_add_f32_e32 v130, v156, v130
	v_add_f32_e32 v130, v157, v130
	v_exp_f32_e32 v195, v131
	v_add_f32_e32 v130, v158, v130
	v_exp_f32_e32 v196, v132
	v_add_f32_e32 v130, v159, v130
	v_exp_f32_e32 v197, v133
	v_add_f32_e32 v130, v160, v130
	v_exp_f32_e32 v198, v134
	v_add_f32_e32 v130, v161, v130
	v_exp_f32_e32 v199, v135
	v_add_f32_e32 v130, v195, v130
	v_exp_f32_e32 v200, v136
	v_add_f32_e32 v130, v196, v130
	v_exp_f32_e32 v201, v137
	v_add_f32_e32 v130, v197, v130
	v_exp_f32_e32 v202, v138
	v_add_f32_e32 v130, v198, v130
	v_exp_f32_e32 v203, v139
	v_add_f32_e32 v130, v199, v130
	v_exp_f32_e32 v204, v140
	v_add_f32_e32 v130, v200, v130
	v_exp_f32_e32 v205, v141
	v_add_f32_e32 v130, v201, v130
	v_exp_f32_e32 v206, v142
	v_add_f32_e32 v130, v202, v130
	v_exp_f32_e32 v207, v143
	v_add_f32_e32 v130, v203, v130
	v_exp_f32_e32 v208, v144
	v_add_f32_e32 v130, v204, v130
	v_exp_f32_e32 v194, v194
	v_add_f32_e32 v130, v205, v130
	v_add_f32_e32 v130, v206, v130
	v_add_f32_e32 v130, v207, v130
	v_add_f32_e32 v130, v208, v130
	v_add_f32_e32 v247, v194, v130
	v_mov_b32_e32 v248, v247
	s_nop 1
	v_permlane32_swap_b32_e32 v247, v248
	v_cvt_pk_bf16_f32 v130, v145, v146
	v_cvt_pk_bf16_f32 v131, v147, v148
	v_cvt_pk_bf16_f32 v132, v149, v150
	v_cvt_pk_bf16_f32 v133, v151, v152
	v_cvt_pk_bf16_f32 v134, v153, v154
	v_cvt_pk_bf16_f32 v135, v155, v156
	v_cvt_pk_bf16_f32 v136, v157, v158
	v_cvt_pk_bf16_f32 v137, v159, v160
	v_cvt_pk_bf16_f32 v138, v161, v195
	v_cvt_pk_bf16_f32 v139, v196, v197
	v_cvt_pk_bf16_f32 v140, v198, v199
	v_cvt_pk_bf16_f32 v141, v200, v201
	v_cvt_pk_bf16_f32 v142, v202, v203
	v_cvt_pk_bf16_f32 v143, v204, v205
	v_cvt_pk_bf16_f32 v144, v206, v207
	v_cvt_pk_bf16_f32 v145, v208, v194
	s_nop 0
	v_permlane32_swap_b32_e32 v130, v132
	v_permlane32_swap_b32_e32 v131, v133
	v_permlane32_swap_b32_e32 v134, v136
	v_permlane32_swap_b32_e32 v135, v137
	v_permlane32_swap_b32_e32 v138, v140
	v_permlane32_swap_b32_e32 v139, v141
	v_permlane32_swap_b32_e32 v142, v144
	v_permlane32_swap_b32_e32 v143, v145
	ds_read_b64_tr_b16 v[146:147], v224 offset:0
	ds_read_b64_tr_b16 v[148:149], v224 offset:0x800
	ds_read_b64_tr_b16 v[150:151], v224 offset:0x1000
	ds_read_b64_tr_b16 v[152:153], v224 offset:0x1800
	ds_read_b64_tr_b16 v[154:155], v224 offset:0x2000
	ds_read_b64_tr_b16 v[156:157], v224 offset:0x2800
	ds_read_b64_tr_b16 v[158:159], v224 offset:0x3000
	ds_read_b64_tr_b16 v[160:161], v224 offset:0x3800
	s_nop 0
	s_waitcnt lgkmcnt(6)
	v_mfma_f32_32x32x16_bf16 v[2:17], v[130:133], v[146:149], v[2:17]
	ds_read_b64_tr_b16 v[146:147], v224 offset:0x200
	ds_read_b64_tr_b16 v[148:149], v224 offset:0xa00
	s_waitcnt lgkmcnt(6)
	v_mfma_f32_32x32x16_bf16 v[2:17], v[134:137], v[150:153], v[2:17]
	ds_read_b64_tr_b16 v[150:151], v224 offset:0x1200
	ds_read_b64_tr_b16 v[152:153], v224 offset:0x1a00
	s_waitcnt lgkmcnt(6)
	v_mfma_f32_32x32x16_bf16 v[2:17], v[138:141], v[154:157], v[2:17]
	ds_read_b64_tr_b16 v[154:155], v224 offset:0x2200
	ds_read_b64_tr_b16 v[156:157], v224 offset:0x2a00
	s_waitcnt lgkmcnt(6)
	v_mfma_f32_32x32x16_bf16 v[2:17], v[142:145], v[158:161], v[2:17]
	ds_read_b64_tr_b16 v[158:159], v224 offset:0x3200
	ds_read_b64_tr_b16 v[160:161], v224 offset:0x3a00
	s_waitcnt lgkmcnt(6)
	v_mfma_f32_32x32x16_bf16 v[114:129], v[130:133], v[146:149], v[114:129]
	ds_read_b64_tr_b16 v[146:147], v224 offset:0x400
	ds_read_b64_tr_b16 v[148:149], v224 offset:0xc00
	s_waitcnt lgkmcnt(6)
	v_mfma_f32_32x32x16_bf16 v[114:129], v[134:137], v[150:153], v[114:129]
	ds_read_b64_tr_b16 v[150:151], v224 offset:0x1400
	ds_read_b64_tr_b16 v[152:153], v224 offset:0x1c00
	s_waitcnt lgkmcnt(6)
	v_mfma_f32_32x32x16_bf16 v[114:129], v[138:141], v[154:157], v[114:129]
	ds_read_b64_tr_b16 v[154:155], v224 offset:0x2400
	ds_read_b64_tr_b16 v[156:157], v224 offset:0x2c00
	s_waitcnt lgkmcnt(6)
	v_mfma_f32_32x32x16_bf16 v[114:129], v[142:145], v[158:161], v[114:129]
	ds_read_b64_tr_b16 v[158:159], v224 offset:0x3400
	ds_read_b64_tr_b16 v[160:161], v224 offset:0x3c00
	s_waitcnt lgkmcnt(6)
	v_mfma_f32_32x32x16_bf16 v[98:113], v[130:133], v[146:149], v[98:113]
	ds_read_b64_tr_b16 v[146:147], v224 offset:0x600
	ds_read_b64_tr_b16 v[148:149], v224 offset:0xe00
	s_waitcnt lgkmcnt(6)
	v_mfma_f32_32x32x16_bf16 v[98:113], v[134:137], v[150:153], v[98:113]
	ds_read_b64_tr_b16 v[150:151], v224 offset:0x1600
	ds_read_b64_tr_b16 v[152:153], v224 offset:0x1e00
	s_waitcnt lgkmcnt(6)
	v_mfma_f32_32x32x16_bf16 v[98:113], v[138:141], v[154:157], v[98:113]
	ds_read_b64_tr_b16 v[154:155], v224 offset:0x2600
	ds_read_b64_tr_b16 v[156:157], v224 offset:0x2e00
	s_waitcnt lgkmcnt(6)
	v_mfma_f32_32x32x16_bf16 v[98:113], v[142:145], v[158:161], v[98:113]
	ds_read_b64_tr_b16 v[158:159], v224 offset:0x3600
	ds_read_b64_tr_b16 v[160:161], v224 offset:0x3e00
	s_waitcnt lgkmcnt(6)
	v_mfma_f32_32x32x16_bf16 v[82:97], v[130:133], v[146:149], v[82:97]
	ds_read_b64_tr_b16 v[146:147], v234 offset:0
	ds_read_b64_tr_b16 v[148:149], v234 offset:0x800
	s_waitcnt lgkmcnt(6)
	v_mfma_f32_32x32x16_bf16 v[82:97], v[134:137], v[150:153], v[82:97]
	ds_read_b64_tr_b16 v[150:151], v234 offset:0x1000
	ds_read_b64_tr_b16 v[152:153], v234 offset:0x1800
	s_waitcnt lgkmcnt(6)
	v_mfma_f32_32x32x16_bf16 v[82:97], v[138:141], v[154:157], v[82:97]
	ds_read_b64_tr_b16 v[154:155], v234 offset:0x2000
	ds_read_b64_tr_b16 v[156:157], v234 offset:0x2800
	s_waitcnt lgkmcnt(6)
	v_mfma_f32_32x32x16_bf16 v[82:97], v[142:145], v[158:161], v[82:97]
	ds_read_b64_tr_b16 v[158:159], v234 offset:0x3000
	ds_read_b64_tr_b16 v[160:161], v234 offset:0x3800
	s_waitcnt lgkmcnt(6)
	v_mfma_f32_32x32x16_bf16 v[66:81], v[130:133], v[146:149], v[66:81]
	ds_read_b64_tr_b16 v[146:147], v234 offset:0x200
	ds_read_b64_tr_b16 v[148:149], v234 offset:0xa00
	s_waitcnt lgkmcnt(6)
	v_mfma_f32_32x32x16_bf16 v[66:81], v[134:137], v[150:153], v[66:81]
	ds_read_b64_tr_b16 v[150:151], v234 offset:0x1200
	ds_read_b64_tr_b16 v[152:153], v234 offset:0x1a00
	s_waitcnt lgkmcnt(6)
	v_mfma_f32_32x32x16_bf16 v[66:81], v[138:141], v[154:157], v[66:81]
	ds_read_b64_tr_b16 v[154:155], v234 offset:0x2200
	ds_read_b64_tr_b16 v[156:157], v234 offset:0x2a00
	s_waitcnt lgkmcnt(6)
	v_mfma_f32_32x32x16_bf16 v[66:81], v[142:145], v[158:161], v[66:81]
	ds_read_b64_tr_b16 v[158:159], v234 offset:0x3200
	ds_read_b64_tr_b16 v[160:161], v234 offset:0x3a00
	s_waitcnt lgkmcnt(6)
	v_mfma_f32_32x32x16_bf16 v[50:65], v[130:133], v[146:149], v[50:65]
	ds_read_b64_tr_b16 v[146:147], v234 offset:0x400
	ds_read_b64_tr_b16 v[148:149], v234 offset:0xc00
	s_waitcnt lgkmcnt(6)
	v_mfma_f32_32x32x16_bf16 v[50:65], v[134:137], v[150:153], v[50:65]
	ds_read_b64_tr_b16 v[150:151], v234 offset:0x1400
	ds_read_b64_tr_b16 v[152:153], v234 offset:0x1c00
	s_waitcnt lgkmcnt(6)
	v_mfma_f32_32x32x16_bf16 v[50:65], v[138:141], v[154:157], v[50:65]
	ds_read_b64_tr_b16 v[154:155], v234 offset:0x2400
	ds_read_b64_tr_b16 v[156:157], v234 offset:0x2c00
	s_waitcnt lgkmcnt(6)
	v_mfma_f32_32x32x16_bf16 v[50:65], v[142:145], v[158:161], v[50:65]
	ds_read_b64_tr_b16 v[158:159], v234 offset:0x3400
	ds_read_b64_tr_b16 v[160:161], v234 offset:0x3c00
	s_waitcnt lgkmcnt(6)
	v_mfma_f32_32x32x16_bf16 v[34:49], v[130:133], v[146:149], v[34:49]
	ds_read_b64_tr_b16 v[146:147], v234 offset:0x600
	ds_read_b64_tr_b16 v[148:149], v234 offset:0xe00
	s_waitcnt lgkmcnt(6)
	v_mfma_f32_32x32x16_bf16 v[34:49], v[134:137], v[150:153], v[34:49]
	ds_read_b64_tr_b16 v[150:151], v234 offset:0x1600
	ds_read_b64_tr_b16 v[152:153], v234 offset:0x1e00
	s_waitcnt lgkmcnt(6)
	v_mfma_f32_32x32x16_bf16 v[34:49], v[138:141], v[154:157], v[34:49]
	ds_read_b64_tr_b16 v[154:155], v234 offset:0x2600
	ds_read_b64_tr_b16 v[156:157], v234 offset:0x2e00
	s_waitcnt lgkmcnt(6)
	v_mfma_f32_32x32x16_bf16 v[34:49], v[142:145], v[158:161], v[34:49]
	ds_read_b64_tr_b16 v[158:159], v234 offset:0x3600
	ds_read_b64_tr_b16 v[160:161], v234 offset:0x3e00
	s_waitcnt lgkmcnt(6)
	v_mfma_f32_32x32x16_bf16 v[18:33], v[130:133], v[146:149], v[18:33]
	s_waitcnt lgkmcnt(0)
	s_barrier
	s_waitcnt lgkmcnt(4)
	v_mfma_f32_32x32x16_bf16 v[18:33], v[134:137], v[150:153], v[18:33]
	s_waitcnt lgkmcnt(2)
	v_mfma_f32_32x32x16_bf16 v[18:33], v[138:141], v[154:157], v[18:33]
	s_waitcnt lgkmcnt(0)
	v_mfma_f32_32x32x16_bf16 v[18:33], v[142:145], v[158:161], v[18:33]
	s_add_i32 s14, s97, -1
	v_lshl_add_u64 v[222:223], v[216:217], 0, s[44:45]
	v_lshl_add_u64 v[220:221], v[218:219], 0, s[44:45]
	s_mov_b64 s[70:71], 0xa0000
	s_waitcnt vmcnt(0)
.LBB0_573:
.LBB0_575:
	s_barrier
	v_readfirstlane_b32 s100, v0
	s_nop 3
	s_cmp_lt_u32 s100, 0x100
	s_cbranch_scc1 .Lstg_2
	s_sleep 12
.Lstg_2:
	ds_read_b128 v[194:197], v238 offset:16384
	ds_read_b128 v[198:201], v239 offset:16384
	ds_read_b128 v[202:205], v238 offset:24576
	ds_read_b128 v[206:209], v239 offset:24576
	s_waitcnt lgkmcnt(3)
	v_mfma_f32_32x32x16_bf16 v[146:161], v[194:197], v[162:165], 0
	ds_read_b128 v[194:197], v240 offset:16384
	s_waitcnt lgkmcnt(3)
	v_mfma_f32_32x32x16_bf16 v[146:161], v[198:201], v[166:169], v[146:161]
	s_cmp_ge_u32 s14, s17
	s_cbranch_scc1 .Lad1b_0
	s_mov_b64 s[100:101], 0x80000
	s_mov_b32 m0, s67
	v_lshl_add_u64 v[250:251], v[222:223], 0, s[100:101]
	global_load_lds_dwordx4 v[250:251], off

.LBB0_579:
	v_cndmask_b32_e64 v249, v251, v249, s[6:7]
	v_mul_f32_e32 v194, 0xbe0293ee, v249
	v_fmamk_f32 v146, v146, 0x3e0293ee, v194
	v_fmamk_f32 v147, v147, 0x3e0293ee, v194
	v_fmamk_f32 v148, v148, 0x3e0293ee, v194
	v_fmamk_f32 v149, v149, 0x3e0293ee, v194
	v_fmamk_f32 v150, v150, 0x3e0293ee, v194
	v_fmamk_f32 v151, v151, 0x3e0293ee, v194
	v_fmamk_f32 v152, v152, 0x3e0293ee, v194
	v_fmamk_f32 v153, v153, 0x3e0293ee, v194
	v_fmamk_f32 v154, v154, 0x3e0293ee, v194
	v_fmamk_f32 v155, v155, 0x3e0293ee, v194
	v_fmamk_f32 v156, v156, 0x3e0293ee, v194
	v_fmamk_f32 v157, v157, 0x3e0293ee, v194
	v_fmamk_f32 v158, v158, 0x3e0293ee, v194
	v_fmamk_f32 v159, v159, 0x3e0293ee, v194
	v_fmamk_f32 v160, v160, 0x3e0293ee, v194
	v_fmamk_f32 v161, v161, 0x3e0293ee, v194
	v_fmamk_f32 v130, v130, 0x3e0293ee, v194
	v_fmamk_f32 v131, v131, 0x3e0293ee, v194
	v_fmamk_f32 v132, v132, 0x3e0293ee, v194
	v_fmamk_f32 v133, v133, 0x3e0293ee, v194
	v_fmamk_f32 v134, v134, 0x3e0293ee, v194
	v_fmamk_f32 v135, v135, 0x3e0293ee, v194
	v_fmamk_f32 v136, v136, 0x3e0293ee, v194
	v_fmamk_f32 v137, v137, 0x3e0293ee, v194
	v_fmamk_f32 v138, v138, 0x3e0293ee, v194
	v_fmamk_f32 v139, v139, 0x3e0293ee, v194
	v_fmamk_f32 v140, v140, 0x3e0293ee, v194
	v_fmamk_f32 v141, v141, 0x3e0293ee, v194
	v_fmamk_f32 v142, v142, 0x3e0293ee, v194
	v_fmamk_f32 v143, v143, 0x3e0293ee, v194
	v_fmamk_f32 v144, v144, 0x3e0293ee, v194
	v_fmac_f32_e32 v194, 0x3e0293ee, v145
	v_exp_f32_e32 v145, v146
	v_exp_f32_e32 v195, v147
	v_exp_f32_e32 v148, v148
	v_exp_f32_e32 v149, v149
	v_exp_f32_e32 v150, v150
	v_exp_f32_e32 v196, v130
	v_add_f32_e32 v130, 0, v145
	v_exp_f32_e32 v151, v151
	v_add_f32_e32 v130, v195, v130
	v_exp_f32_e32 v152, v152
	v_add_f32_e32 v130, v148, v130
	v_exp_f32_e32 v153, v153
	v_add_f32_e32 v130, v149, v130
	v_exp_f32_e32 v154, v154
	v_add_f32_e32 v130, v150, v130
	v_exp_f32_e32 v155, v155
	v_add_f32_e32 v130, v151, v130
	v_exp_f32_e32 v156, v156
	v_add_f32_e32 v130, v152, v130
	v_exp_f32_e32 v157, v157
	v_add_f32_e32 v130, v153, v130
	v_exp_f32_e32 v158, v158
	v_add_f32_e32 v130, v154, v130
	v_exp_f32_e32 v159, v159
	v_add_f32_e32 v130, v155, v130
	v_exp_f32_e32 v160, v160
	v_add_f32_e32 v130, v156, v130
	v_exp_f32_e32 v161, v161
	v_add_f32_e32 v130, v157, v130
	v_add_f32_e32 v130, v158, v130
	v_exp_f32_e32 v197, v131
	v_add_f32_e32 v130, v159, v130
	v_exp_f32_e32 v198, v132
	v_add_f32_e32 v130, v160, v130
	v_exp_f32_e32 v199, v133
	v_add_f32_e32 v130, v161, v130
	v_exp_f32_e32 v200, v134
	v_add_f32_e32 v130, v196, v130
	v_exp_f32_e32 v201, v135
	v_add_f32_e32 v130, v197, v130
	v_exp_f32_e32 v202, v136
	v_add_f32_e32 v130, v198, v130
	v_exp_f32_e32 v203, v137
	v_add_f32_e32 v130, v199, v130
	v_exp_f32_e32 v204, v138
	v_add_f32_e32 v130, v200, v130
	v_exp_f32_e32 v205, v139
	v_add_f32_e32 v130, v201, v130
	v_exp_f32_e32 v206, v140
	v_add_f32_e32 v130, v202, v130
	v_exp_f32_e32 v207, v141
	v_add_f32_e32 v130, v203, v130
	v_exp_f32_e32 v208, v142
	v_add_f32_e32 v130, v204, v130
	v_exp_f32_e32 v209, v143
	v_add_f32_e32 v130, v205, v130
	v_exp_f32_e32 v251, v144
	v_add_f32_e32 v130, v206, v130
	v_exp_f32_e32 v194, v194
	v_add_f32_e32 v130, v207, v130
	v_add_f32_e32 v130, v208, v130
	v_add_f32_e32 v130, v209, v130
	v_add_f32_e32 v130, v251, v130
	v_add_f32_e32 v146, v194, v130
	v_mov_b32_e32 v147, v146
	s_nop 1
	v_permlane32_swap_b32_e32 v146, v147
	v_cvt_pk_bf16_f32 v130, v145, v195
	v_cvt_pk_bf16_f32 v131, v148, v149
	v_cvt_pk_bf16_f32 v132, v150, v151
	v_cvt_pk_bf16_f32 v133, v152, v153
	v_cvt_pk_bf16_f32 v134, v154, v155
	v_cvt_pk_bf16_f32 v135, v156, v157
	v_cvt_pk_bf16_f32 v136, v158, v159
	v_cvt_pk_bf16_f32 v137, v160, v161
	v_cvt_pk_bf16_f32 v138, v196, v197
	v_cvt_pk_bf16_f32 v139, v198, v199
	v_cvt_pk_bf16_f32 v140, v200, v201
	v_cvt_pk_bf16_f32 v141, v202, v203
	v_cvt_pk_bf16_f32 v142, v204, v205
	v_cvt_pk_bf16_f32 v143, v206, v207
	v_cvt_pk_bf16_f32 v144, v208, v209
	v_cvt_pk_bf16_f32 v145, v251, v194
	s_nop 0
	v_permlane32_swap_b32_e32 v130, v132
	v_permlane32_swap_b32_e32 v131, v133
	v_permlane32_swap_b32_e32 v134, v136
	v_permlane32_swap_b32_e32 v135, v137
	v_permlane32_swap_b32_e32 v138, v140
	v_permlane32_swap_b32_e32 v139, v141
	v_permlane32_swap_b32_e32 v142, v144
	v_permlane32_swap_b32_e32 v143, v145
	ds_read_b64_tr_b16 v[148:149], v235 offset:0
	ds_read_b64_tr_b16 v[150:151], v235 offset:0x800
	ds_read_b64_tr_b16 v[152:153], v235 offset:0x1000
	ds_read_b64_tr_b16 v[154:155], v235 offset:0x1800
	ds_read_b64_tr_b16 v[156:157], v235 offset:0x2000
	ds_read_b64_tr_b16 v[158:159], v235 offset:0x2800
	ds_read_b64_tr_b16 v[194:195], v235 offset:0x3000
	ds_read_b64_tr_b16 v[196:197], v235 offset:0x3800
	s_nop 0
	s_waitcnt lgkmcnt(6)
	v_mfma_f32_32x32x16_bf16 v[2:17], v[130:133], v[148:151], v[2:17]
	ds_read_b64_tr_b16 v[148:149], v235 offset:0x200
	ds_read_b64_tr_b16 v[150:151], v235 offset:0xa00
	s_waitcnt lgkmcnt(6)
	v_mfma_f32_32x32x16_bf16 v[2:17], v[134:137], v[152:155], v[2:17]
	ds_read_b64_tr_b16 v[152:153], v235 offset:0x1200
	ds_read_b64_tr_b16 v[154:155], v235 offset:0x1a00
	s_waitcnt lgkmcnt(6)
	v_mfma_f32_32x32x16_bf16 v[2:17], v[138:141], v[156:159], v[2:17]
	ds_read_b64_tr_b16 v[156:157], v235 offset:0x2200
	ds_read_b64_tr_b16 v[158:159], v235 offset:0x2a00
	s_waitcnt lgkmcnt(6)
	v_mfma_f32_32x32x16_bf16 v[2:17], v[142:145], v[194:197], v[2:17]
	ds_read_b64_tr_b16 v[194:195], v235 offset:0x3200
	ds_read_b64_tr_b16 v[196:197], v235 offset:0x3a00
	s_waitcnt lgkmcnt(6)
	v_mfma_f32_32x32x16_bf16 v[114:129], v[130:133], v[148:151], v[114:129]
	ds_read_b64_tr_b16 v[148:149], v235 offset:0x400
	ds_read_b64_tr_b16 v[150:151], v235 offset:0xc00
	s_waitcnt lgkmcnt(6)
	v_mfma_f32_32x32x16_bf16 v[114:129], v[134:137], v[152:155], v[114:129]
	ds_read_b64_tr_b16 v[152:153], v235 offset:0x1400
	ds_read_b64_tr_b16 v[154:155], v235 offset:0x1c00
	s_waitcnt lgkmcnt(6)
	v_mfma_f32_32x32x16_bf16 v[114:129], v[138:141], v[156:159], v[114:129]
	ds_read_b64_tr_b16 v[156:157], v235 offset:0x2400
	ds_read_b64_tr_b16 v[158:159], v235 offset:0x2c00
	s_waitcnt lgkmcnt(6)
	v_mfma_f32_32x32x16_bf16 v[114:129], v[142:145], v[194:197], v[114:129]
	ds_read_b64_tr_b16 v[194:195], v235 offset:0x3400
	ds_read_b64_tr_b16 v[196:197], v235 offset:0x3c00
	s_waitcnt lgkmcnt(6)
	v_mfma_f32_32x32x16_bf16 v[98:113], v[130:133], v[148:151], v[98:113]
	ds_read_b64_tr_b16 v[148:149], v235 offset:0x600
	ds_read_b64_tr_b16 v[150:151], v235 offset:0xe00
	s_waitcnt lgkmcnt(6)
	v_mfma_f32_32x32x16_bf16 v[98:113], v[134:137], v[152:155], v[98:113]
	ds_read_b64_tr_b16 v[152:153], v235 offset:0x1600
	ds_read_b64_tr_b16 v[154:155], v235 offset:0x1e00
	s_waitcnt lgkmcnt(6)
	v_mfma_f32_32x32x16_bf16 v[98:113], v[138:141], v[156:159], v[98:113]
	ds_read_b64_tr_b16 v[156:157], v235 offset:0x2600
	ds_read_b64_tr_b16 v[158:159], v235 offset:0x2e00
	s_waitcnt lgkmcnt(6)
	v_mfma_f32_32x32x16_bf16 v[98:113], v[142:145], v[194:197], v[98:113]
	ds_read_b64_tr_b16 v[194:195], v235 offset:0x3600
	ds_read_b64_tr_b16 v[196:197], v235 offset:0x3e00
	s_waitcnt lgkmcnt(6)
	v_mfma_f32_32x32x16_bf16 v[82:97], v[130:133], v[148:151], v[82:97]
	ds_read_b64_tr_b16 v[148:149], v236 offset:0
	ds_read_b64_tr_b16 v[150:151], v236 offset:0x800
	s_waitcnt lgkmcnt(6)
	v_mfma_f32_32x32x16_bf16 v[82:97], v[134:137], v[152:155], v[82:97]
	ds_read_b64_tr_b16 v[152:153], v236 offset:0x1000
	ds_read_b64_tr_b16 v[154:155], v236 offset:0x1800
	s_waitcnt lgkmcnt(6)
	v_mfma_f32_32x32x16_bf16 v[82:97], v[138:141], v[156:159], v[82:97]
	ds_read_b64_tr_b16 v[156:157], v236 offset:0x2000
	ds_read_b64_tr_b16 v[158:159], v236 offset:0x2800
	s_waitcnt lgkmcnt(6)
	v_mfma_f32_32x32x16_bf16 v[82:97], v[142:145], v[194:197], v[82:97]
	ds_read_b64_tr_b16 v[194:195], v236 offset:0x3000
	ds_read_b64_tr_b16 v[196:197], v236 offset:0x3800
	s_waitcnt lgkmcnt(6)
	v_mfma_f32_32x32x16_bf16 v[66:81], v[130:133], v[148:151], v[66:81]
	ds_read_b64_tr_b16 v[148:149], v236 offset:0x200
	ds_read_b64_tr_b16 v[150:151], v236 offset:0xa00
	s_waitcnt lgkmcnt(6)
	v_mfma_f32_32x32x16_bf16 v[66:81], v[134:137], v[152:155], v[66:81]
	ds_read_b64_tr_b16 v[152:153], v236 offset:0x1200
	ds_read_b64_tr_b16 v[154:155], v236 offset:0x1a00
	s_waitcnt lgkmcnt(6)
	v_mfma_f32_32x32x16_bf16 v[66:81], v[138:141], v[156:159], v[66:81]
	ds_read_b64_tr_b16 v[156:157], v236 offset:0x2200
	ds_read_b64_tr_b16 v[158:159], v236 offset:0x2a00
	s_waitcnt lgkmcnt(6)
	v_mfma_f32_32x32x16_bf16 v[66:81], v[142:145], v[194:197], v[66:81]
	ds_read_b64_tr_b16 v[194:195], v236 offset:0x3200
	ds_read_b64_tr_b16 v[196:197], v236 offset:0x3a00
	s_waitcnt lgkmcnt(6)
	v_mfma_f32_32x32x16_bf16 v[50:65], v[130:133], v[148:151], v[50:65]
	ds_read_b64_tr_b16 v[148:149], v236 offset:0x400
	ds_read_b64_tr_b16 v[150:151], v236 offset:0xc00
	s_waitcnt lgkmcnt(6)
	v_mfma_f32_32x32x16_bf16 v[50:65], v[134:137], v[152:155], v[50:65]
	ds_read_b64_tr_b16 v[152:153], v236 offset:0x1400
	ds_read_b64_tr_b16 v[154:155], v236 offset:0x1c00
	s_waitcnt lgkmcnt(6)
	v_mfma_f32_32x32x16_bf16 v[50:65], v[138:141], v[156:159], v[50:65]
	ds_read_b64_tr_b16 v[156:157], v236 offset:0x2400
	ds_read_b64_tr_b16 v[158:159], v236 offset:0x2c00
	s_waitcnt lgkmcnt(6)
	v_mfma_f32_32x32x16_bf16 v[50:65], v[142:145], v[194:197], v[50:65]
	ds_read_b64_tr_b16 v[194:195], v236 offset:0x3400
	ds_read_b64_tr_b16 v[196:197], v236 offset:0x3c00
	s_waitcnt lgkmcnt(6)
	v_mfma_f32_32x32x16_bf16 v[34:49], v[130:133], v[148:151], v[34:49]
	ds_read_b64_tr_b16 v[148:149], v236 offset:0x600
	ds_read_b64_tr_b16 v[150:151], v236 offset:0xe00
	s_waitcnt lgkmcnt(6)
	v_mfma_f32_32x32x16_bf16 v[34:49], v[134:137], v[152:155], v[34:49]
	ds_read_b64_tr_b16 v[152:153], v236 offset:0x1600
	ds_read_b64_tr_b16 v[154:155], v236 offset:0x1e00
	s_waitcnt lgkmcnt(6)
	v_mfma_f32_32x32x16_bf16 v[34:49], v[138:141], v[156:159], v[34:49]
	ds_read_b64_tr_b16 v[156:157], v236 offset:0x2600
	ds_read_b64_tr_b16 v[158:159], v236 offset:0x2e00
	s_waitcnt lgkmcnt(6)
	v_mfma_f32_32x32x16_bf16 v[34:49], v[142:145], v[194:197], v[34:49]
	ds_read_b64_tr_b16 v[194:195], v236 offset:0x3600
	ds_read_b64_tr_b16 v[196:197], v236 offset:0x3e00
	s_waitcnt lgkmcnt(6)
	v_mfma_f32_32x32x16_bf16 v[18:33], v[130:133], v[148:151], v[18:33]
	s_waitcnt lgkmcnt(0)
	s_barrier
	s_waitcnt lgkmcnt(4)
	v_mfma_f32_32x32x16_bf16 v[18:33], v[134:137], v[152:155], v[18:33]
	s_waitcnt lgkmcnt(2)
	v_mfma_f32_32x32x16_bf16 v[18:33], v[138:141], v[156:159], v[18:33]
	s_waitcnt lgkmcnt(0)
	v_mfma_f32_32x32x16_bf16 v[18:33], v[142:145], v[194:197], v[18:33]
	s_branch .LBB0_562

.Lstg_3:
	ds_read_b128 v[194:197], v238
	ds_read_b128 v[198:201], v239
	ds_read_b128 v[202:205], v238 offset:8192
	ds_read_b128 v[206:209], v239 offset:8192
	s_waitcnt lgkmcnt(3)
	v_mfma_f32_32x32x16_bf16 v[146:161], v[194:197], v[162:165], 0
	ds_read_b128 v[194:197], v240
	s_waitcnt lgkmcnt(3)
	v_mfma_f32_32x32x16_bf16 v[146:161], v[198:201], v[166:169], v[146:161]
	s_cmp_lt_u32 s51, 5
	s_cbranch_scc1 .Lad2a_0
	s_mov_b64 s[100:101], 0xc0100
	s_mov_b32 m0, s42
	v_lshl_add_u64 v[250:251], v[222:223], 0, s[100:101]
	global_load_lds_dwordx4 v[250:251], off

.LBB0_593:
	v_cndmask_b32_e64 v249, v220, v249, s[6:7]
	v_mul_f32_e32 v194, 0xbe0293ee, v249
	v_fmamk_f32 v146, v146, 0x3e0293ee, v194
	v_fmamk_f32 v147, v147, 0x3e0293ee, v194
	v_fmamk_f32 v148, v148, 0x3e0293ee, v194
	v_fmamk_f32 v149, v149, 0x3e0293ee, v194
	v_fmamk_f32 v150, v150, 0x3e0293ee, v194
	v_fmamk_f32 v151, v151, 0x3e0293ee, v194
	v_fmamk_f32 v152, v152, 0x3e0293ee, v194
	v_fmamk_f32 v153, v153, 0x3e0293ee, v194
	v_fmamk_f32 v154, v154, 0x3e0293ee, v194
	v_fmamk_f32 v155, v155, 0x3e0293ee, v194
	v_fmamk_f32 v156, v156, 0x3e0293ee, v194
	v_fmamk_f32 v157, v157, 0x3e0293ee, v194
	v_fmamk_f32 v158, v158, 0x3e0293ee, v194
	v_fmamk_f32 v159, v159, 0x3e0293ee, v194
	v_fmamk_f32 v160, v160, 0x3e0293ee, v194
	v_fmamk_f32 v161, v161, 0x3e0293ee, v194
	v_fmamk_f32 v130, v130, 0x3e0293ee, v194
	v_fmamk_f32 v131, v131, 0x3e0293ee, v194
	v_fmamk_f32 v132, v132, 0x3e0293ee, v194
	v_fmamk_f32 v133, v133, 0x3e0293ee, v194
	v_fmamk_f32 v134, v134, 0x3e0293ee, v194
	v_fmamk_f32 v135, v135, 0x3e0293ee, v194
	v_fmamk_f32 v136, v136, 0x3e0293ee, v194
	v_fmamk_f32 v137, v137, 0x3e0293ee, v194
	v_fmamk_f32 v138, v138, 0x3e0293ee, v194
	v_fmamk_f32 v139, v139, 0x3e0293ee, v194
	v_fmamk_f32 v140, v140, 0x3e0293ee, v194
	v_fmamk_f32 v141, v141, 0x3e0293ee, v194
	v_fmamk_f32 v142, v142, 0x3e0293ee, v194
	v_fmamk_f32 v143, v143, 0x3e0293ee, v194
	v_fmamk_f32 v144, v144, 0x3e0293ee, v194
	v_fmac_f32_e32 v194, 0x3e0293ee, v145
	v_exp_f32_e32 v145, v146
	v_exp_f32_e32 v146, v147
	v_exp_f32_e32 v147, v148
	v_exp_f32_e32 v148, v149
	v_exp_f32_e32 v149, v150
	v_exp_f32_e32 v150, v151
	v_exp_f32_e32 v151, v152
	v_exp_f32_e32 v152, v153
	v_exp_f32_e32 v153, v154
	v_exp_f32_e32 v154, v155
	v_exp_f32_e32 v155, v156
	v_exp_f32_e32 v156, v157
	v_exp_f32_e32 v157, v158
	v_exp_f32_e32 v158, v159
	v_exp_f32_e32 v159, v160
	v_exp_f32_e32 v160, v161
	v_exp_f32_e32 v161, v130
	v_add_f32_e32 v130, 0, v145
	v_add_f32_e32 v130, v146, v130
	v_add_f32_e32 v130, v147, v130
	v_add_f32_e32 v130, v148, v130
	v_add_f32_e32 v130, v149, v130
	v_add_f32_e32 v130, v150, v130
	v_add_f32_e32 v130, v151, v130
	v_add_f32_e32 v130, v152, v130
	v_add_f32_e32 v130, v153, v130
	v_add_f32_e32 v130, v154, v130
	v_add_f32_e32 v130, v155, v130
	v_add_f32_e32 v130, v156, v130
	v_add_f32_e32 v130, v157, v130
	v_exp_f32_e32 v195, v131
	v_add_f32_e32 v130, v158, v130
	v_exp_f32_e32 v196, v132
	v_add_f32_e32 v130, v159, v130
	v_exp_f32_e32 v197, v133
	v_add_f32_e32 v130, v160, v130
	v_exp_f32_e32 v198, v134
	v_add_f32_e32 v130, v161, v130
	v_exp_f32_e32 v199, v135
	v_add_f32_e32 v130, v195, v130
	v_exp_f32_e32 v200, v136
	v_add_f32_e32 v130, v196, v130
	v_exp_f32_e32 v201, v137
	v_add_f32_e32 v130, v197, v130
	v_exp_f32_e32 v202, v138
	v_add_f32_e32 v130, v198, v130
	v_exp_f32_e32 v203, v139
	v_add_f32_e32 v130, v199, v130
	v_exp_f32_e32 v204, v140
	v_add_f32_e32 v130, v200, v130
	v_exp_f32_e32 v205, v141
	v_add_f32_e32 v130, v201, v130
	v_exp_f32_e32 v206, v142
	v_add_f32_e32 v130, v202, v130
	v_exp_f32_e32 v207, v143
	v_add_f32_e32 v130, v203, v130
	v_exp_f32_e32 v208, v144
	v_add_f32_e32 v130, v204, v130
	v_exp_f32_e32 v194, v194
	v_add_f32_e32 v130, v205, v130
	v_add_f32_e32 v130, v206, v130
	v_add_f32_e32 v130, v207, v130
	v_add_f32_e32 v130, v208, v130
	v_add_f32_e32 v247, v194, v130
	v_mov_b32_e32 v248, v247
	s_nop 1
	v_permlane32_swap_b32_e32 v247, v248
	v_cvt_pk_bf16_f32 v130, v145, v146
	v_cvt_pk_bf16_f32 v131, v147, v148
	v_cvt_pk_bf16_f32 v132, v149, v150
	v_cvt_pk_bf16_f32 v133, v151, v152
	v_cvt_pk_bf16_f32 v134, v153, v154
	v_cvt_pk_bf16_f32 v135, v155, v156
	v_cvt_pk_bf16_f32 v136, v157, v158
	v_cvt_pk_bf16_f32 v137, v159, v160
	v_cvt_pk_bf16_f32 v138, v161, v195
	v_cvt_pk_bf16_f32 v139, v196, v197
	v_cvt_pk_bf16_f32 v140, v198, v199
	v_cvt_pk_bf16_f32 v141, v200, v201
	v_cvt_pk_bf16_f32 v142, v202, v203
	v_cvt_pk_bf16_f32 v143, v204, v205
	v_cvt_pk_bf16_f32 v144, v206, v207
	v_cvt_pk_bf16_f32 v145, v208, v194
	s_nop 0
	v_permlane32_swap_b32_e32 v130, v132
	v_permlane32_swap_b32_e32 v131, v133
	v_permlane32_swap_b32_e32 v134, v136
	v_permlane32_swap_b32_e32 v135, v137
	v_permlane32_swap_b32_e32 v138, v140
	v_permlane32_swap_b32_e32 v139, v141
	v_permlane32_swap_b32_e32 v142, v144
	v_permlane32_swap_b32_e32 v143, v145
	ds_read_b64_tr_b16 v[146:147], v224 offset:0
	ds_read_b64_tr_b16 v[148:149], v224 offset:0x800
	ds_read_b64_tr_b16 v[150:151], v224 offset:0x1000
	ds_read_b64_tr_b16 v[152:153], v224 offset:0x1800
	ds_read_b64_tr_b16 v[154:155], v224 offset:0x2000
	ds_read_b64_tr_b16 v[156:157], v224 offset:0x2800
	ds_read_b64_tr_b16 v[158:159], v224 offset:0x3000
	ds_read_b64_tr_b16 v[160:161], v224 offset:0x3800
	s_nop 0
	s_waitcnt lgkmcnt(6)
	v_mfma_f32_32x32x16_bf16 v[2:17], v[130:133], v[146:149], v[2:17]
	ds_read_b64_tr_b16 v[146:147], v224 offset:0x200
	ds_read_b64_tr_b16 v[148:149], v224 offset:0xa00
	s_waitcnt lgkmcnt(6)
	v_mfma_f32_32x32x16_bf16 v[2:17], v[134:137], v[150:153], v[2:17]
	ds_read_b64_tr_b16 v[150:151], v224 offset:0x1200
	ds_read_b64_tr_b16 v[152:153], v224 offset:0x1a00
	s_waitcnt lgkmcnt(6)
	v_mfma_f32_32x32x16_bf16 v[2:17], v[138:141], v[154:157], v[2:17]
	ds_read_b64_tr_b16 v[154:155], v224 offset:0x2200
	ds_read_b64_tr_b16 v[156:157], v224 offset:0x2a00
	s_waitcnt lgkmcnt(6)
	v_mfma_f32_32x32x16_bf16 v[2:17], v[142:145], v[158:161], v[2:17]
	ds_read_b64_tr_b16 v[158:159], v224 offset:0x3200
	ds_read_b64_tr_b16 v[160:161], v224 offset:0x3a00
	s_waitcnt lgkmcnt(6)
	v_mfma_f32_32x32x16_bf16 v[18:33], v[130:133], v[146:149], v[18:33]
	ds_read_b64_tr_b16 v[146:147], v224 offset:0x400
	ds_read_b64_tr_b16 v[148:149], v224 offset:0xc00
	s_waitcnt lgkmcnt(6)
	v_mfma_f32_32x32x16_bf16 v[18:33], v[134:137], v[150:153], v[18:33]
	ds_read_b64_tr_b16 v[150:151], v224 offset:0x1400
	ds_read_b64_tr_b16 v[152:153], v224 offset:0x1c00
	s_waitcnt lgkmcnt(6)
	v_mfma_f32_32x32x16_bf16 v[18:33], v[138:141], v[154:157], v[18:33]
	ds_read_b64_tr_b16 v[154:155], v224 offset:0x2400
	ds_read_b64_tr_b16 v[156:157], v224 offset:0x2c00
	s_waitcnt lgkmcnt(6)
	v_mfma_f32_32x32x16_bf16 v[18:33], v[142:145], v[158:161], v[18:33]
	ds_read_b64_tr_b16 v[158:159], v224 offset:0x3400
	ds_read_b64_tr_b16 v[160:161], v224 offset:0x3c00
	s_waitcnt lgkmcnt(6)
	v_mfma_f32_32x32x16_bf16 v[34:49], v[130:133], v[146:149], v[34:49]
	ds_read_b64_tr_b16 v[146:147], v224 offset:0x600
	ds_read_b64_tr_b16 v[148:149], v224 offset:0xe00
	s_waitcnt lgkmcnt(6)
	v_mfma_f32_32x32x16_bf16 v[34:49], v[134:137], v[150:153], v[34:49]
	ds_read_b64_tr_b16 v[150:151], v224 offset:0x1600
	ds_read_b64_tr_b16 v[152:153], v224 offset:0x1e00
	s_waitcnt lgkmcnt(6)
	v_mfma_f32_32x32x16_bf16 v[34:49], v[138:141], v[154:157], v[34:49]
	ds_read_b64_tr_b16 v[154:155], v224 offset:0x2600
	ds_read_b64_tr_b16 v[156:157], v224 offset:0x2e00
	s_waitcnt lgkmcnt(6)
	v_mfma_f32_32x32x16_bf16 v[34:49], v[142:145], v[158:161], v[34:49]
	ds_read_b64_tr_b16 v[158:159], v224 offset:0x3600
	ds_read_b64_tr_b16 v[160:161], v224 offset:0x3e00
	s_waitcnt lgkmcnt(6)
	v_mfma_f32_32x32x16_bf16 v[50:65], v[130:133], v[146:149], v[50:65]
	ds_read_b64_tr_b16 v[146:147], v234 offset:0
	ds_read_b64_tr_b16 v[148:149], v234 offset:0x800
	s_waitcnt lgkmcnt(6)
	v_mfma_f32_32x32x16_bf16 v[50:65], v[134:137], v[150:153], v[50:65]
	ds_read_b64_tr_b16 v[150:151], v234 offset:0x1000
	ds_read_b64_tr_b16 v[152:153], v234 offset:0x1800
	s_waitcnt lgkmcnt(6)
	v_mfma_f32_32x32x16_bf16 v[50:65], v[138:141], v[154:157], v[50:65]
	ds_read_b64_tr_b16 v[154:155], v234 offset:0x2000
	ds_read_b64_tr_b16 v[156:157], v234 offset:0x2800
	s_waitcnt lgkmcnt(6)
	v_mfma_f32_32x32x16_bf16 v[50:65], v[142:145], v[158:161], v[50:65]
	ds_read_b64_tr_b16 v[158:159], v234 offset:0x3000
	ds_read_b64_tr_b16 v[160:161], v234 offset:0x3800
	s_waitcnt lgkmcnt(6)
	v_mfma_f32_32x32x16_bf16 v[66:81], v[130:133], v[146:149], v[66:81]
	ds_read_b64_tr_b16 v[146:147], v234 offset:0x200
	ds_read_b64_tr_b16 v[148:149], v234 offset:0xa00
	s_waitcnt lgkmcnt(6)
	v_mfma_f32_32x32x16_bf16 v[66:81], v[134:137], v[150:153], v[66:81]
	ds_read_b64_tr_b16 v[150:151], v234 offset:0x1200
	ds_read_b64_tr_b16 v[152:153], v234 offset:0x1a00
	s_waitcnt lgkmcnt(6)
	v_mfma_f32_32x32x16_bf16 v[66:81], v[138:141], v[154:157], v[66:81]
	ds_read_b64_tr_b16 v[154:155], v234 offset:0x2200
	ds_read_b64_tr_b16 v[156:157], v234 offset:0x2a00
	s_waitcnt lgkmcnt(6)
	v_mfma_f32_32x32x16_bf16 v[66:81], v[142:145], v[158:161], v[66:81]
	ds_read_b64_tr_b16 v[158:159], v234 offset:0x3200
	ds_read_b64_tr_b16 v[160:161], v234 offset:0x3a00
	s_waitcnt lgkmcnt(6)
	v_mfma_f32_32x32x16_bf16 v[82:97], v[130:133], v[146:149], v[82:97]
	ds_read_b64_tr_b16 v[146:147], v234 offset:0x400
	ds_read_b64_tr_b16 v[148:149], v234 offset:0xc00
	s_waitcnt lgkmcnt(6)
	v_mfma_f32_32x32x16_bf16 v[82:97], v[134:137], v[150:153], v[82:97]
	ds_read_b64_tr_b16 v[150:151], v234 offset:0x1400
	ds_read_b64_tr_b16 v[152:153], v234 offset:0x1c00
	s_waitcnt lgkmcnt(6)
	v_mfma_f32_32x32x16_bf16 v[82:97], v[138:141], v[154:157], v[82:97]
	ds_read_b64_tr_b16 v[154:155], v234 offset:0x2400
	ds_read_b64_tr_b16 v[156:157], v234 offset:0x2c00
	s_waitcnt lgkmcnt(6)
	v_mfma_f32_32x32x16_bf16 v[82:97], v[142:145], v[158:161], v[82:97]
	ds_read_b64_tr_b16 v[158:159], v234 offset:0x3400
	ds_read_b64_tr_b16 v[160:161], v234 offset:0x3c00
	s_waitcnt lgkmcnt(6)
	v_mfma_f32_32x32x16_bf16 v[98:113], v[130:133], v[146:149], v[98:113]
	ds_read_b64_tr_b16 v[146:147], v234 offset:0x600
	ds_read_b64_tr_b16 v[148:149], v234 offset:0xe00
	s_waitcnt lgkmcnt(6)
	v_mfma_f32_32x32x16_bf16 v[98:113], v[134:137], v[150:153], v[98:113]
	ds_read_b64_tr_b16 v[150:151], v234 offset:0x1600
	ds_read_b64_tr_b16 v[152:153], v234 offset:0x1e00
	s_waitcnt lgkmcnt(6)
	v_mfma_f32_32x32x16_bf16 v[98:113], v[138:141], v[154:157], v[98:113]
	ds_read_b64_tr_b16 v[154:155], v234 offset:0x2600
	ds_read_b64_tr_b16 v[156:157], v234 offset:0x2e00
	s_waitcnt lgkmcnt(6)
	v_mfma_f32_32x32x16_bf16 v[98:113], v[142:145], v[158:161], v[98:113]
	ds_read_b64_tr_b16 v[158:159], v234 offset:0x3600
	ds_read_b64_tr_b16 v[160:161], v234 offset:0x3e00
	s_waitcnt lgkmcnt(6)
	v_mfma_f32_32x32x16_bf16 v[114:129], v[130:133], v[146:149], v[114:129]
	s_waitcnt lgkmcnt(0)
	s_barrier
	s_waitcnt lgkmcnt(4)
	v_mfma_f32_32x32x16_bf16 v[114:129], v[134:137], v[150:153], v[114:129]
	s_waitcnt lgkmcnt(2)
	v_mfma_f32_32x32x16_bf16 v[114:129], v[138:141], v[154:157], v[114:129]
	s_waitcnt lgkmcnt(0)
	v_mfma_f32_32x32x16_bf16 v[114:129], v[142:145], v[158:161], v[114:129]
	s_add_i32 s2, s51, -1
	v_lshl_add_u64 v[222:223], v[216:217], 0, s[44:45]
	v_lshl_add_u64 v[220:221], v[218:219], 0, s[44:45]
	s_waitcnt vmcnt(0)

.Lstg_4:
	ds_read_b128 v[194:197], v238 offset:16384
	ds_read_b128 v[198:201], v239 offset:16384
	ds_read_b128 v[202:205], v238 offset:24576
	ds_read_b128 v[206:209], v239 offset:24576
	s_waitcnt lgkmcnt(3)
	v_mfma_f32_32x32x16_bf16 v[146:161], v[194:197], v[162:165], 0
	ds_read_b128 v[194:197], v240 offset:16384
	s_waitcnt lgkmcnt(3)
	v_mfma_f32_32x32x16_bf16 v[146:161], v[198:201], v[166:169], v[146:161]
	s_cmp_ge_u32 s2, s17
	s_cbranch_scc1 .Lad2b_0
	s_mov_b64 s[100:101], 0x80100
	s_mov_b32 m0, s38
	v_lshl_add_u64 v[250:251], v[222:223], 0, s[100:101]
	global_load_lds_dwordx4 v[250:251], off

.LBB0_601:
	v_cndmask_b32_e64 v249, v251, v249, s[6:7]
	v_mul_f32_e32 v194, 0xbe0293ee, v249
	v_fmamk_f32 v146, v146, 0x3e0293ee, v194
	v_fmamk_f32 v147, v147, 0x3e0293ee, v194
	v_fmamk_f32 v148, v148, 0x3e0293ee, v194
	v_fmamk_f32 v149, v149, 0x3e0293ee, v194
	v_fmamk_f32 v150, v150, 0x3e0293ee, v194
	v_fmamk_f32 v151, v151, 0x3e0293ee, v194
	v_fmamk_f32 v152, v152, 0x3e0293ee, v194
	v_fmamk_f32 v153, v153, 0x3e0293ee, v194
	v_fmamk_f32 v154, v154, 0x3e0293ee, v194
	v_fmamk_f32 v155, v155, 0x3e0293ee, v194
	v_fmamk_f32 v156, v156, 0x3e0293ee, v194
	v_fmamk_f32 v157, v157, 0x3e0293ee, v194
	v_fmamk_f32 v158, v158, 0x3e0293ee, v194
	v_fmamk_f32 v159, v159, 0x3e0293ee, v194
	v_fmamk_f32 v160, v160, 0x3e0293ee, v194
	v_fmamk_f32 v161, v161, 0x3e0293ee, v194
	v_fmamk_f32 v130, v130, 0x3e0293ee, v194
	v_fmamk_f32 v131, v131, 0x3e0293ee, v194
	v_fmamk_f32 v132, v132, 0x3e0293ee, v194
	v_fmamk_f32 v133, v133, 0x3e0293ee, v194
	v_fmamk_f32 v134, v134, 0x3e0293ee, v194
	v_fmamk_f32 v135, v135, 0x3e0293ee, v194
	v_fmamk_f32 v136, v136, 0x3e0293ee, v194
	v_fmamk_f32 v137, v137, 0x3e0293ee, v194
	v_fmamk_f32 v138, v138, 0x3e0293ee, v194
	v_fmamk_f32 v139, v139, 0x3e0293ee, v194
	v_fmamk_f32 v140, v140, 0x3e0293ee, v194
	v_fmamk_f32 v141, v141, 0x3e0293ee, v194
	v_fmamk_f32 v142, v142, 0x3e0293ee, v194
	v_fmamk_f32 v143, v143, 0x3e0293ee, v194
	v_fmamk_f32 v144, v144, 0x3e0293ee, v194
	v_fmac_f32_e32 v194, 0x3e0293ee, v145
	v_exp_f32_e32 v145, v146
	v_exp_f32_e32 v195, v147
	v_exp_f32_e32 v148, v148
	v_exp_f32_e32 v149, v149
	v_exp_f32_e32 v150, v150
	v_exp_f32_e32 v196, v130
	v_add_f32_e32 v130, 0, v145
	v_exp_f32_e32 v151, v151
	v_add_f32_e32 v130, v195, v130
	v_exp_f32_e32 v152, v152
	v_add_f32_e32 v130, v148, v130
	v_exp_f32_e32 v153, v153
	v_add_f32_e32 v130, v149, v130
	v_exp_f32_e32 v154, v154
	v_add_f32_e32 v130, v150, v130
	v_exp_f32_e32 v155, v155
	v_add_f32_e32 v130, v151, v130
	v_exp_f32_e32 v156, v156
	v_add_f32_e32 v130, v152, v130
	v_exp_f32_e32 v157, v157
	v_add_f32_e32 v130, v153, v130
	v_exp_f32_e32 v158, v158
	v_add_f32_e32 v130, v154, v130
	v_exp_f32_e32 v159, v159
	v_add_f32_e32 v130, v155, v130
	v_exp_f32_e32 v160, v160
	v_add_f32_e32 v130, v156, v130
	v_exp_f32_e32 v161, v161
	v_add_f32_e32 v130, v157, v130
	v_add_f32_e32 v130, v158, v130
	v_exp_f32_e32 v197, v131
	v_add_f32_e32 v130, v159, v130
	v_exp_f32_e32 v198, v132
	v_add_f32_e32 v130, v160, v130
	v_exp_f32_e32 v199, v133
	v_add_f32_e32 v130, v161, v130
	v_exp_f32_e32 v200, v134
	v_add_f32_e32 v130, v196, v130
	v_exp_f32_e32 v201, v135
	v_add_f32_e32 v130, v197, v130
	v_exp_f32_e32 v202, v136
	v_add_f32_e32 v130, v198, v130
	v_exp_f32_e32 v203, v137
	v_add_f32_e32 v130, v199, v130
	v_exp_f32_e32 v204, v138
	v_add_f32_e32 v130, v200, v130
	v_exp_f32_e32 v205, v139
	v_add_f32_e32 v130, v201, v130
	v_exp_f32_e32 v206, v140
	v_add_f32_e32 v130, v202, v130
	v_exp_f32_e32 v207, v141
	v_add_f32_e32 v130, v203, v130
	v_exp_f32_e32 v208, v142
	v_add_f32_e32 v130, v204, v130
	v_exp_f32_e32 v209, v143
	v_add_f32_e32 v130, v205, v130
	v_exp_f32_e32 v251, v144
	v_add_f32_e32 v130, v206, v130
	v_exp_f32_e32 v194, v194
	v_add_f32_e32 v130, v207, v130
	v_add_f32_e32 v130, v208, v130
	v_add_f32_e32 v130, v209, v130
	v_add_f32_e32 v130, v251, v130
	v_add_f32_e32 v146, v194, v130
	v_mov_b32_e32 v147, v146
	s_nop 1
	v_permlane32_swap_b32_e32 v146, v147
	v_cvt_pk_bf16_f32 v130, v145, v195
	v_cvt_pk_bf16_f32 v131, v148, v149
	v_cvt_pk_bf16_f32 v132, v150, v151
	v_cvt_pk_bf16_f32 v133, v152, v153
	v_cvt_pk_bf16_f32 v134, v154, v155
	v_cvt_pk_bf16_f32 v135, v156, v157
	v_cvt_pk_bf16_f32 v136, v158, v159
	v_cvt_pk_bf16_f32 v137, v160, v161
	v_cvt_pk_bf16_f32 v138, v196, v197
	v_cvt_pk_bf16_f32 v139, v198, v199
	v_cvt_pk_bf16_f32 v140, v200, v201
	v_cvt_pk_bf16_f32 v141, v202, v203
	v_cvt_pk_bf16_f32 v142, v204, v205
	v_cvt_pk_bf16_f32 v143, v206, v207
	v_cvt_pk_bf16_f32 v144, v208, v209
	v_cvt_pk_bf16_f32 v145, v251, v194
	s_nop 0
	v_permlane32_swap_b32_e32 v130, v132
	v_permlane32_swap_b32_e32 v131, v133
	v_permlane32_swap_b32_e32 v134, v136
	v_permlane32_swap_b32_e32 v135, v137
	v_permlane32_swap_b32_e32 v138, v140
	v_permlane32_swap_b32_e32 v139, v141
	v_permlane32_swap_b32_e32 v142, v144
	v_permlane32_swap_b32_e32 v143, v145
	ds_read_b64_tr_b16 v[148:149], v235 offset:0
	ds_read_b64_tr_b16 v[150:151], v235 offset:0x800
	ds_read_b64_tr_b16 v[152:153], v235 offset:0x1000
	ds_read_b64_tr_b16 v[154:155], v235 offset:0x1800
	ds_read_b64_tr_b16 v[156:157], v235 offset:0x2000
	ds_read_b64_tr_b16 v[158:159], v235 offset:0x2800
	ds_read_b64_tr_b16 v[194:195], v235 offset:0x3000
	ds_read_b64_tr_b16 v[196:197], v235 offset:0x3800
	s_nop 0
	s_waitcnt lgkmcnt(6)
	v_mfma_f32_32x32x16_bf16 v[2:17], v[130:133], v[148:151], v[2:17]
	ds_read_b64_tr_b16 v[148:149], v235 offset:0x200
	ds_read_b64_tr_b16 v[150:151], v235 offset:0xa00
	s_waitcnt lgkmcnt(6)
	v_mfma_f32_32x32x16_bf16 v[2:17], v[134:137], v[152:155], v[2:17]
	ds_read_b64_tr_b16 v[152:153], v235 offset:0x1200
	ds_read_b64_tr_b16 v[154:155], v235 offset:0x1a00
	s_waitcnt lgkmcnt(6)
	v_mfma_f32_32x32x16_bf16 v[2:17], v[138:141], v[156:159], v[2:17]
	ds_read_b64_tr_b16 v[156:157], v235 offset:0x2200
	ds_read_b64_tr_b16 v[158:159], v235 offset:0x2a00
	s_waitcnt lgkmcnt(6)
	v_mfma_f32_32x32x16_bf16 v[2:17], v[142:145], v[194:197], v[2:17]
	ds_read_b64_tr_b16 v[194:195], v235 offset:0x3200
	ds_read_b64_tr_b16 v[196:197], v235 offset:0x3a00
	s_waitcnt lgkmcnt(6)
	v_mfma_f32_32x32x16_bf16 v[18:33], v[130:133], v[148:151], v[18:33]
	ds_read_b64_tr_b16 v[148:149], v235 offset:0x400
	ds_read_b64_tr_b16 v[150:151], v235 offset:0xc00
	s_waitcnt lgkmcnt(6)
	v_mfma_f32_32x32x16_bf16 v[18:33], v[134:137], v[152:155], v[18:33]
	ds_read_b64_tr_b16 v[152:153], v235 offset:0x1400
	ds_read_b64_tr_b16 v[154:155], v235 offset:0x1c00
	s_waitcnt lgkmcnt(6)
	v_mfma_f32_32x32x16_bf16 v[18:33], v[138:141], v[156:159], v[18:33]
	ds_read_b64_tr_b16 v[156:157], v235 offset:0x2400
	ds_read_b64_tr_b16 v[158:159], v235 offset:0x2c00
	s_waitcnt lgkmcnt(6)
	v_mfma_f32_32x32x16_bf16 v[18:33], v[142:145], v[194:197], v[18:33]
	ds_read_b64_tr_b16 v[194:195], v235 offset:0x3400
	ds_read_b64_tr_b16 v[196:197], v235 offset:0x3c00
	s_waitcnt lgkmcnt(6)
	v_mfma_f32_32x32x16_bf16 v[34:49], v[130:133], v[148:151], v[34:49]
	ds_read_b64_tr_b16 v[148:149], v235 offset:0x600
	ds_read_b64_tr_b16 v[150:151], v235 offset:0xe00
	s_waitcnt lgkmcnt(6)
	v_mfma_f32_32x32x16_bf16 v[34:49], v[134:137], v[152:155], v[34:49]
	ds_read_b64_tr_b16 v[152:153], v235 offset:0x1600
	ds_read_b64_tr_b16 v[154:155], v235 offset:0x1e00
	s_waitcnt lgkmcnt(6)
	v_mfma_f32_32x32x16_bf16 v[34:49], v[138:141], v[156:159], v[34:49]
	ds_read_b64_tr_b16 v[156:157], v235 offset:0x2600
	ds_read_b64_tr_b16 v[158:159], v235 offset:0x2e00
	s_waitcnt lgkmcnt(6)
	v_mfma_f32_32x32x16_bf16 v[34:49], v[142:145], v[194:197], v[34:49]
	ds_read_b64_tr_b16 v[194:195], v235 offset:0x3600
	ds_read_b64_tr_b16 v[196:197], v235 offset:0x3e00
	s_waitcnt lgkmcnt(6)
	v_mfma_f32_32x32x16_bf16 v[50:65], v[130:133], v[148:151], v[50:65]
	ds_read_b64_tr_b16 v[148:149], v236 offset:0
	ds_read_b64_tr_b16 v[150:151], v236 offset:0x800
	s_waitcnt lgkmcnt(6)
	v_mfma_f32_32x32x16_bf16 v[50:65], v[134:137], v[152:155], v[50:65]
	ds_read_b64_tr_b16 v[152:153], v236 offset:0x1000
	ds_read_b64_tr_b16 v[154:155], v236 offset:0x1800
	s_waitcnt lgkmcnt(6)
	v_mfma_f32_32x32x16_bf16 v[50:65], v[138:141], v[156:159], v[50:65]
	ds_read_b64_tr_b16 v[156:157], v236 offset:0x2000
	ds_read_b64_tr_b16 v[158:159], v236 offset:0x2800
	s_waitcnt lgkmcnt(6)
	v_mfma_f32_32x32x16_bf16 v[50:65], v[142:145], v[194:197], v[50:65]
	ds_read_b64_tr_b16 v[194:195], v236 offset:0x3000
	ds_read_b64_tr_b16 v[196:197], v236 offset:0x3800
	s_waitcnt lgkmcnt(6)
	v_mfma_f32_32x32x16_bf16 v[66:81], v[130:133], v[148:151], v[66:81]
	ds_read_b64_tr_b16 v[148:149], v236 offset:0x200
	ds_read_b64_tr_b16 v[150:151], v236 offset:0xa00
	s_waitcnt lgkmcnt(6)
	v_mfma_f32_32x32x16_bf16 v[66:81], v[134:137], v[152:155], v[66:81]
	ds_read_b64_tr_b16 v[152:153], v236 offset:0x1200
	ds_read_b64_tr_b16 v[154:155], v236 offset:0x1a00
	s_waitcnt lgkmcnt(6)
	v_mfma_f32_32x32x16_bf16 v[66:81], v[138:141], v[156:159], v[66:81]
	ds_read_b64_tr_b16 v[156:157], v236 offset:0x2200
	ds_read_b64_tr_b16 v[158:159], v236 offset:0x2a00
	s_waitcnt lgkmcnt(6)
	v_mfma_f32_32x32x16_bf16 v[66:81], v[142:145], v[194:197], v[66:81]
	ds_read_b64_tr_b16 v[194:195], v236 offset:0x3200
	ds_read_b64_tr_b16 v[196:197], v236 offset:0x3a00
	s_waitcnt lgkmcnt(6)
	v_mfma_f32_32x32x16_bf16 v[82:97], v[130:133], v[148:151], v[82:97]
	ds_read_b64_tr_b16 v[148:149], v236 offset:0x400
	ds_read_b64_tr_b16 v[150:151], v236 offset:0xc00
	s_waitcnt lgkmcnt(6)
	v_mfma_f32_32x32x16_bf16 v[82:97], v[134:137], v[152:155], v[82:97]
	ds_read_b64_tr_b16 v[152:153], v236 offset:0x1400
	ds_read_b64_tr_b16 v[154:155], v236 offset:0x1c00
	s_waitcnt lgkmcnt(6)
	v_mfma_f32_32x32x16_bf16 v[82:97], v[138:141], v[156:159], v[82:97]
	ds_read_b64_tr_b16 v[156:157], v236 offset:0x2400
	ds_read_b64_tr_b16 v[158:159], v236 offset:0x2c00
	s_waitcnt lgkmcnt(6)
	v_mfma_f32_32x32x16_bf16 v[82:97], v[142:145], v[194:197], v[82:97]
	ds_read_b64_tr_b16 v[194:195], v236 offset:0x3400
	ds_read_b64_tr_b16 v[196:197], v236 offset:0x3c00
	s_waitcnt lgkmcnt(6)
	v_mfma_f32_32x32x16_bf16 v[98:113], v[130:133], v[148:151], v[98:113]
	ds_read_b64_tr_b16 v[148:149], v236 offset:0x600
	ds_read_b64_tr_b16 v[150:151], v236 offset:0xe00
	s_waitcnt lgkmcnt(6)
	v_mfma_f32_32x32x16_bf16 v[98:113], v[134:137], v[152:155], v[98:113]
	ds_read_b64_tr_b16 v[152:153], v236 offset:0x1600
	ds_read_b64_tr_b16 v[154:155], v236 offset:0x1e00
	s_waitcnt lgkmcnt(6)
	v_mfma_f32_32x32x16_bf16 v[98:113], v[138:141], v[156:159], v[98:113]
	ds_read_b64_tr_b16 v[156:157], v236 offset:0x2600
	ds_read_b64_tr_b16 v[158:159], v236 offset:0x2e00
	s_waitcnt lgkmcnt(6)
	v_mfma_f32_32x32x16_bf16 v[98:113], v[142:145], v[194:197], v[98:113]
	ds_read_b64_tr_b16 v[194:195], v236 offset:0x3600
	ds_read_b64_tr_b16 v[196:197], v236 offset:0x3e00
	s_waitcnt lgkmcnt(6)
	v_mfma_f32_32x32x16_bf16 v[114:129], v[130:133], v[148:151], v[114:129]
	s_waitcnt lgkmcnt(0)
	s_barrier
	s_waitcnt lgkmcnt(4)
	v_mfma_f32_32x32x16_bf16 v[114:129], v[134:137], v[152:155], v[114:129]
	s_waitcnt lgkmcnt(2)
	v_mfma_f32_32x32x16_bf16 v[114:129], v[138:141], v[156:159], v[114:129]
	s_waitcnt lgkmcnt(0)
	v_mfma_f32_32x32x16_bf16 v[114:129], v[142:145], v[194:197], v[114:129]
	s_mov_b64 s[80:81], 0xc0100
	s_mov_b64 s[82:83], 0xe0100
	s_branch .LBB0_584
